# v29 + nt on the last reads of the residual stream (final norm) and of the scan outputs Y (mixer post pass)
# baseline (speedup 1.0000x reference)
; __device__ __forceinline__ void unpack8bf(const u32x4 w, float* f) { f[0] = bflo(w.x); f[1] = bfhi(w.x); f[2] = bflo(w.y); f[3] = bfhi(w.y); f[4] = bflo(w.z); f[5] = bfhi(w.z); f[6] = bflo(w.w); f[7] = bfhi(w.w); }
; __device__ __forceinline__ float sum8(float v) { v += __shfl_xor(v, 1); v += __shfl_xor(v, 2); v += __shfl_xor(v, 4); return v; }
; __device__ __forceinline__ void p10_row(const P& p, int row, int lane) {
;     ...
;     { const int c = lane * 8; const int pos = seq_pos(row), L = row < TP ? 8192 : 16384; const bool hasp = pos > 0, hasn = pos < L - 1;
;       const float* mu = p.in[13];
;       const bf16_t* zr = (const bf16_t*)(ws + WS_ZRKV) + (size_t)row * 1536 + c;
;       float v[8];
;       shift8(zr + 1024, 1536, hasp, hasn, mu + 1024 + c, mu + 1920 + 1024 + c, v);
;       float g[8]; unpack8bf(*(const u32x4*)(mix + 512 + c), g);
;       const bf16_t* yp = (const bf16_t*)(ws + WS_Y) + (size_t)row * 512 + c;
;       float y[8], yb2[8]; unpack8bf(*(const u32x4*)yp, y); unpack8bf(*(const u32x4*)(yp + (size_t)T * 512), yb2);
; #pragma unroll
;       for (int e = 0; e < 8; ++e) y[e] += yb2[e];
;       float s = 0.f;
; #pragma unroll
;       for (int e = 0; e < 8; ++e) s += y[e];
;       const float mean = sum8(s) * (1.f / 64.f); float q = 0.f;
; #pragma unroll
;       for (int e = 0; e < 8; ++e) { y[e] -= mean; q += y[e] * y[e]; }
.LBB0_1169:
	v_lshl_add_u64 v[6:7], s[50:51], 0, v[38:39]
	v_add_co_u32_e32 v8, vcc, s16, v6
	global_load_dwordx4 v[64:67], v[30:31], off
	global_load_dwordx4 v[68:71], v[28:29], off
	global_load_dwordx4 v[14:17], v[30:31], off offset:16
	global_load_dwordx4 v[10:13], v[28:29], off offset:16
	v_addc_co_u32_e32 v9, vcc, 0, v7, vcc
	v_add_co_u32_e32 v6, vcc, s17, v6
	s_waitcnt vmcnt(4)
	v_lshlrev_b32_e32 v47, 16, v23
	v_addc_co_u32_e32 v7, vcc, 0, v7, vcc
	global_load_dwordx4 v[72:75], v[6:7], off nt
	global_load_dwordx4 v[76:79], v[8:9], off nt
	v_add_co_u32_e32 v44, vcc, s3, v4
	v_lshlrev_b32_e32 v8, 16, v22
	s_nop 0
	v_addc_co_u32_e32 v45, vcc, 0, v5, vcc
	global_load_dwordx4 v[4:7], v[44:45], off offset:1024
	v_and_b32_e32 v9, 0xffff0000, v22
	v_and_b32_e32 v51, 0xffff0000, v23
	v_lshlrev_b32_e32 v63, 16, v24
	v_and_b32_e32 v80, 0xffff0000, v24
	v_lshlrev_b32_e32 v83, 16, v0
	v_lshlrev_b32_e32 v24, 16, v18
	v_and_b32_e32 v23, 0xffff0000, v18
	v_and_b32_e32 v22, 0xffff0000, v0
	v_lshlrev_b32_e32 v84, 16, v1
	v_and_b32_e32 v18, 0xffff0000, v1
	v_lshl_add_u64 v[0:1], s[50:51], 0, v[36:37]
	v_lshlrev_b32_e32 v50, 16, v20
	v_and_b32_e32 v49, 0xffff0000, v20
	v_lshlrev_b32_e32 v20, 16, v21
	v_and_b32_e32 v81, 0xffff0000, v21
	v_sub_f32_e32 v21, v8, v24
	v_add_co_u32_e32 v8, vcc, s18, v0
	v_sub_f32_e32 v86, v9, v23
	s_nop 0
	v_addc_co_u32_e32 v9, vcc, 0, v1, vcc
	v_lshlrev_b32_e32 v85, 16, v2
	v_and_b32_e32 v48, 0xffff0000, v2
	v_add_co_u32_e32 v0, vcc, s19, v0
	v_sub_f32_e32 v63, v63, v50
	v_sub_f32_e32 v85, v85, v50
	v_sub_f32_e32 v93, v48, v49
	v_addc_co_u32_e32 v1, vcc, 0, v1, vcc
	global_load_dword v99, v[8:9], off
	s_nop 0
	global_load_dword v1, v[0:1], off
	v_lshlrev_b32_e32 v2, 16, v3
	v_lshlrev_b32_e32 v46, 16, v19
	v_and_b32_e32 v19, 0xffff0000, v19
	v_sub_f32_e32 v2, v2, v20
	v_lshlrev_b32_e32 v82, 16, v25
	v_sub_f32_e32 v47, v47, v46
	v_sub_f32_e32 v51, v51, v19
	v_sub_f32_e32 v89, v84, v46
	v_sub_f32_e32 v95, v82, v20
	v_sub_f32_e32 v80, v80, v49
	v_cmp_lt_i32_e32 vcc, v57, v56
	v_sub_f32_e32 v83, v83, v24
	v_sub_f32_e32 v87, v22, v23
	v_sub_f32_e32 v91, v18, v19
	v_and_b32_e32 v25, 0xffff0000, v25
	s_add_i32 s20, s20, s88
	v_lshl_add_u64 v[36:37], v[36:37], 0, s[4:5]
	v_lshl_add_u64 v[38:39], v[38:39], 0, s[8:9]
	v_lshl_add_u64 v[40:41], v[40:41], 0, s[10:11]
	s_cmp_gt_i32 s20, 0xbfff
	v_lshl_add_u64 v[42:43], v[42:43], 0, s[12:13]
	s_waitcnt vmcnt(8)
	v_mul_f32_e32 v82, v21, v64
	v_mul_f32_e32 v84, v86, v65
	s_waitcnt vmcnt(6)
	v_mul_f32_e32 v96, v63, v14
	s_waitcnt vmcnt(5)
	v_mul_f32_e32 v98, v85, v10
	v_mul_f32_e32 v14, v93, v11
	v_mul_f32_e32 v2, v2, v12
	v_mul_f32_e32 v88, v47, v66
	v_mul_f32_e32 v92, v51, v67
	v_mul_f32_e32 v100, v80, v15
	v_mul_f32_e32 v0, v68, v83
	s_waitcnt vmcnt(4)
	v_lshlrev_b32_e32 v9, 16, v72
	s_waitcnt vmcnt(3)
	v_lshlrev_b32_e32 v11, 16, v76
	v_and_b32_e32 v8, 0xffff0000, v72
	v_and_b32_e32 v10, 0xffff0000, v76
	v_pk_add_f32 v[102:103], v[10:11], v[8:9]
	v_lshlrev_b32_e32 v9, 16, v73
	v_lshlrev_b32_e32 v11, 16, v77
	v_and_b32_e32 v8, 0xffff0000, v73
	v_and_b32_e32 v10, 0xffff0000, v77
	v_pk_add_f32 v[76:77], v[10:11], v[8:9]
	v_lshlrev_b32_e32 v9, 16, v74
	v_lshlrev_b32_e32 v11, 16, v78
	v_and_b32_e32 v8, 0xffff0000, v74
	v_and_b32_e32 v10, 0xffff0000, v78
	v_pk_add_f32 v[104:105], v[10:11], v[8:9]
	global_load_dwordx4 v[8:11], v[32:33], off offset:16
	v_add_f32_e32 v12, 0, v103
	v_lshlrev_b32_e32 v65, 16, v75
	v_lshlrev_b32_e32 v67, 16, v79
	v_and_b32_e32 v64, 0xffff0000, v75
	v_and_b32_e32 v66, 0xffff0000, v79
	v_add_f32_e32 v12, v102, v12
	v_pk_add_f32 v[78:79], v[66:67], v[64:65]
	v_add_f32_e32 v12, v77, v12
	global_load_dwordx4 v[64:67], v[32:33], off
	v_add_f32_e32 v12, v76, v12
	v_add_f32_e32 v12, v105, v12
	v_add_f32_e32 v12, v104, v12
	v_add_f32_e32 v12, v79, v12
	v_add_f32_e32 v15, v78, v12
	v_cndmask_b32_e32 v12, v54, v57, vcc
	v_lshlrev_b32_e32 v63, 2, v12
	ds_bpermute_b32 v21, v63, v15
	v_mul_f32_e32 v86, v87, v69
	v_mul_f32_e32 v90, v89, v70
	v_mul_f32_e32 v94, v91, v71
	global_load_dwordx4 v[68:71], v[34:35], off offset:16
	global_load_dwordx4 v[72:75], v[34:35], off
	v_and_b32_e32 v80, 0xffff0000, v3
	v_sub_f32_e32 v3, v25, v81
	v_cmp_lt_i32_e32 vcc, v58, v56
	v_mul_f32_e32 v12, v3, v17
	s_waitcnt lgkmcnt(0)
	v_add_f32_e32 v15, v15, v21
	v_cndmask_b32_e32 v17, v54, v58, vcc
	v_lshlrev_b32_e32 v83, 2, v17
	ds_bpermute_b32 v17, v83, v15
	v_sub_f32_e32 v3, v80, v81
	v_cmp_lt_i32_e32 vcc, v59, v56
	v_mul_f32_e32 v106, v3, v13
	s_waitcnt vmcnt(6)
	v_lshlrev_b32_e32 v3, 16, v4
	v_cndmask_b32_e32 v13, v54, v59, vcc
	v_and_b32_e32 v91, 0xffff0000, v4
	s_waitcnt lgkmcnt(0)
	v_add_f32_e32 v4, v15, v17
	v_lshlrev_b32_e32 v15, 2, v13
	ds_bpermute_b32 v13, v15, v4
	v_mul_f32_e32 v16, v95, v16
	v_mov_b32_e32 v17, v79
	v_lshlrev_b32_e32 v93, 16, v5
	v_and_b32_e32 v107, 0xffff0000, v5
	s_waitcnt lgkmcnt(0)
; __device__ __forceinline__ unsigned pkbf(float lo, float hi) { return pg8::cvt_pk_bf16(lo, hi); }
; __device__ __forceinline__ void unpack8bf(const u32x4 w, float* f) { f[0] = bflo(w.x); f[1] = bfhi(w.x); f[2] = bflo(w.y); f[3] = bfhi(w.y); f[4] = bflo(w.z); f[5] = bfhi(w.z); f[6] = bflo(w.w); f[7] = bfhi(w.w); }
; __device__ __forceinline__ float sum8(float v) { v += __shfl_xor(v, 1); v += __shfl_xor(v, 2); v += __shfl_xor(v, 4); return v; }
; __device__ __forceinline__ void p10_row(const P& p, int row, int lane) {
;     ...
;       shift8(zr + 1024, 1536, hasp, hasn, mu + 1024 + c, mu + 1920 + 1024 + c, v);
;       float g[8]; unpack8bf(*(const u32x4*)(mix + 512 + c), g);
;       const bf16_t* yp = (const bf16_t*)(ws + WS_Y) + (size_t)row * 512 + c;
;       float y[8], yb2[8]; unpack8bf(*(const u32x4*)yp, y); unpack8bf(*(const u32x4*)(yp + (size_t)T * 512), yb2);
; #pragma unroll
;       for (int e = 0; e < 8; ++e) y[e] += yb2[e];
;       float s = 0.f;
; #pragma unroll
;       for (int e = 0; e < 8; ++e) s += y[e];
;       const float mean = sum8(s) * (1.f / 64.f); float q = 0.f;
; #pragma unroll
;       for (int e = 0; e < 8; ++e) { y[e] -= mean; q += y[e] * y[e]; }
;       const float rstd = 1.0f / sqrtf(sum8(q) * (1.f / 64.f) + LNX_EPS);
;       const float* lw = p.in[22] + c; const float* lb = p.in[23] + c;
;       const float* bsp = (const float*)(ws + WS_BS) + (size_t)row * 8 + (lane >> 3);
;       const float bs = bsp[0] + bsp[(size_t)T * 8];
;       float o[8];
; #pragma unroll
;       for (int e = 0; e < 8; ++e) o[e] = (y[e] * rstd * lw[e] + lb[e] + bs * v[e]) * g[e];
;       u32x4 w; w.x = pkbf(o[0], o[1]); w.y = pkbf(o[2], o[3]); w.z = pkbf(o[4], o[5]); w.w = pkbf(o[6], o[7]);
;       *(u32x4*)(mix + 512 + c) = w; }
	v_add_f32_e32 v4, v4, v13
	v_mul_f32_e32 v21, 0x3c800000, v4
	v_pk_add_f32 v[4:5], v[16:17], v[20:21]
	v_pk_add_f32 v[16:17], v[16:17], v[20:21] neg_lo:[0,1] neg_hi:[0,1]
	v_mov_b32_e32 v13, v78
	v_mov_b32_e32 v20, v81
	v_pk_add_f32 v[78:79], v[12:13], v[20:21] neg_lo:[0,1] neg_hi:[0,1]
	v_mov_b32_e32 v101, v104
	v_mov_b32_e32 v20, v49
	v_mov_b32_e32 v97, v105
	v_pk_add_f32 v[104:105], v[100:101], v[20:21] neg_lo:[0,1] neg_hi:[0,1]
	v_mov_b32_e32 v20, v19
	v_mov_b32_e32 v25, v21
	v_pk_add_f32 v[116:117], v[76:77], v[20:21] op_sel_hi:[0,1] neg_lo:[0,1] neg_hi:[0,1]
	v_pk_add_f32 v[118:119], v[102:103], v[24:25] neg_lo:[0,1] neg_hi:[0,1]
	v_mov_b32_e32 v20, v23
	v_lshlrev_b32_e32 v120, 16, v6
	v_and_b32_e32 v121, 0xffff0000, v6
	v_mov_b32_e32 v51, v21
	v_mov_b32_e32 v47, v21
	v_pk_add_f32 v[20:21], v[102:103], v[20:21] op_sel_hi:[0,1] neg_lo:[0,1] neg_hi:[0,1]
	v_mul_f32_e32 v6, v119, v119
	v_pk_add_f32 v[110:111], v[96:97], v[50:51] neg_lo:[0,1] neg_hi:[0,1]
	v_pk_add_f32 v[114:115], v[76:77], v[46:47] neg_lo:[0,1] neg_hi:[0,1]
	v_fmac_f32_e32 v6, v21, v21
	v_mov_b32_e32 v112, v105
	v_mov_b32_e32 v113, v111
	v_fmac_f32_e32 v6, v115, v115
	v_pk_mul_f32 v[112:113], v[112:113], v[112:113]
	v_fmac_f32_e32 v6, v117, v117
	v_mov_b32_e32 v108, v79
	v_mov_b32_e32 v109, v17
	v_add_f32_e32 v6, v113, v6
	v_pk_mul_f32 v[108:109], v[108:109], v[108:109]
	v_add_f32_e32 v6, v112, v6
	v_add_f32_e32 v6, v109, v6
	v_add_f32_e32 v76, v108, v6
	ds_bpermute_b32 v63, v63, v76
	s_waitcnt vmcnt(4)
	v_add_f32_e32 v6, v99, v1
	v_lshlrev_b32_e32 v122, 16, v7
	v_and_b32_e32 v102, 0xffff0000, v7
	s_waitcnt vmcnt(3)
	v_mov_b32_e32 v7, v10
	s_waitcnt lgkmcnt(0)
	v_add_f32_e32 v1, v76, v63
	ds_bpermute_b32 v10, v83, v1
	v_pk_add_f32 v[12:13], v[12:13], v[80:81] op_sel:[0,1] op_sel_hi:[1,0]
	v_mov_b32_e32 v81, v8
	v_mov_b32_e32 v83, v103
	v_pk_add_f32 v[24:25], v[82:83], v[24:25]
	s_waitcnt lgkmcnt(0)
	v_add_f32_e32 v1, v1, v10
	ds_bpermute_b32 v8, v15, v1
	s_waitcnt vmcnt(2)
	v_mov_b32_e32 v83, v64
	v_pk_add_f32 v[22:23], v[84:85], v[22:23] op_sel:[0,1] op_sel_hi:[1,0]
	v_mov_b32_e32 v82, v6
	v_mov_b32_e32 v89, v77
	s_waitcnt lgkmcnt(0)
	v_add_f32_e32 v1, v1, v8
	v_fmamk_f32 v1, v1, 0x3c800000, v55
	v_mul_f32_e32 v8, 0x4f800000, v1
	v_cmp_gt_f32_e32 vcc, s14, v1
	v_pk_add_f32 v[46:47], v[88:89], v[46:47]
	v_mov_b32_e32 v76, v6
	v_cndmask_b32_e32 v1, v1, v8, vcc
	v_sqrt_f32_e32 v8, v1
	v_mov_b32_e32 v77, v66
	v_pk_add_f32 v[18:19], v[92:93], v[18:19] op_sel:[0,1] op_sel_hi:[1,0]
	v_mov_b32_e32 v66, v6
	v_add_u32_e32 v10, -1, v8
	v_fma_f32 v15, -v10, v8, v1
	v_cmp_ge_f32_e64 s[0:1], 0, v15
	v_add_u32_e32 v15, 1, v8
	v_pk_add_f32 v[50:51], v[96:97], v[50:51]
	v_cndmask_b32_e64 v10, v8, v10, s[0:1]
	v_fma_f32 v8, -v15, v8, v1
	v_cmp_lt_f32_e64 s[0:1], 0, v8
	v_mov_b32_e32 v80, v6
	v_pk_add_f32 v[48:49], v[100:101], v[48:49] op_sel:[0,1] op_sel_hi:[1,0]
	v_cndmask_b32_e64 v8, v10, v15, s[0:1]
	v_mul_f32_e32 v10, 0x37800000, v8
	v_cndmask_b32_e32 v8, v8, v10, vcc
	v_cmp_class_f32_e32 vcc, v1, v53
	s_nop 1
	v_cndmask_b32_e32 v1, v8, v1, vcc
	v_div_scale_f32 v8, s[0:1], v1, v1, 1.0
	v_rcp_f32_e32 v10, v8
	s_nop 0
	v_fma_f32 v15, -v8, v10, 1.0
	v_fmac_f32_e32 v10, v15, v10
	v_div_scale_f32 v15, vcc, 1.0, v1, 1.0
	v_mul_f32_e32 v63, v15, v10
	v_fma_f32 v64, -v8, v63, v15
	v_fmac_f32_e32 v63, v64, v10
	v_fma_f32 v8, -v8, v63, v15
	v_div_fmas_f32 v8, v8, v10, v63
	v_div_fixup_f32 v1, v8, v1, 1.0
	v_pk_add_f32 v[24:25], v[24:25], v[0:1]
	v_pk_mul_f32 v[84:85], v[118:119], v[0:1]
	v_mov_b32_e32 v87, v1
	v_mov_b32_e32 v25, v85
	v_pk_mul_f32 v[24:25], v[82:83], v[24:25]
	v_pk_add_f32 v[22:23], v[22:23], v[86:87]
	v_pk_mul_f32 v[20:21], v[20:21], v[86:87]
	s_waitcnt vmcnt(0)
	v_add_f32_e32 v0, v72, v25
	v_mov_b32_e32 v23, v21
	v_mov_b32_e32 v64, v6
	v_add_f32_e32 v0, v24, v0
	v_pk_mul_f32 v[20:21], v[64:65], v[22:23]
	v_mul_f32_e32 v10, v0, v3
	v_add_f32_e32 v0, v73, v21
	v_add_f32_e32 v0, v20, v0
	v_mul_f32_e32 v24, v0, v91
	v_mov_b32_e32 v91, v1
	v_pk_add_f32 v[20:21], v[46:47], v[90:91]
	v_pk_mul_f32 v[22:23], v[114:115], v[90:91]
	v_mov_b32_e32 v95, v1
	v_mov_b32_e32 v21, v23
	v_pk_mul_f32 v[20:21], v[76:77], v[20:21]
	v_pk_add_f32 v[18:19], v[18:19], v[94:95]
	v_add_f32_e32 v0, v74, v21
	v_add_f32_e32 v0, v20, v0
	v_pk_mul_f32 v[20:21], v[116:117], v[94:95]
	v_mul_f32_e32 v22, v0, v93
	v_mov_b32_e32 v19, v21
	v_pk_mul_f32 v[18:19], v[66:67], v[18:19]
	v_mov_b32_e32 v99, v1
	v_add_f32_e32 v0, v75, v19
	v_add_f32_e32 v0, v18, v0
	v_pk_add_f32 v[18:19], v[50:51], v[98:99]
	v_pk_mul_f32 v[20:21], v[110:111], v[98:99]
	v_mul_f32_e32 v23, v0, v107
	v_mov_b32_e32 v19, v21
	v_pk_mul_f32 v[18:19], v[80:81], v[18:19]
	v_mov_b32_e32 v15, v1
	v_add_f32_e32 v0, v68, v19
	v_add_f32_e32 v0, v18, v0
	v_pk_add_f32 v[18:19], v[48:49], v[14:15]
	v_pk_mul_f32 v[14:15], v[104:105], v[14:15]
	v_mov_b32_e32 v8, v6
	v_mov_b32_e32 v19, v15
	v_mov_b32_e32 v3, v1
	v_pk_mul_f32 v[8:9], v[8:9], v[18:19]
	v_pk_add_f32 v[4:5], v[4:5], v[2:3]
	v_pk_mul_f32 v[2:3], v[16:17], v[2:3]
	v_mul_f32_e32 v20, v0, v120
	v_add_f32_e32 v0, v69, v9
	v_mov_b32_e32 v5, v3
	v_add_f32_e32 v0, v8, v0
	v_pk_mul_f32 v[2:3], v[6:7], v[4:5]
	v_mul_f32_e32 v8, v0, v121
	v_add_f32_e32 v0, v70, v3
	v_add_f32_e32 v0, v2, v0
	v_mov_b32_e32 v107, v1
	v_mul_f32_e32 v4, v0, v122
	v_pk_add_f32 v[0:1], v[12:13], v[106:107]
	v_pk_mul_f32 v[2:3], v[78:79], v[106:107]
	v_mov_b32_e32 v7, v11
	v_mov_b32_e32 v1, v3
	v_pk_mul_f32 v[0:1], v[6:7], v[0:1]
	s_nop 0
	v_add_f32_e32 v1, v71, v1
	v_add_f32_e32 v0, v0, v1
	v_mul_f32_e32 v3, v0, v102
	v_cvt_pk_bf16_f32 v0, v10, v24
	v_cvt_pk_bf16_f32 v1, v22, v23
	v_cvt_pk_bf16_f32 v2, v20, v8
	v_cvt_pk_bf16_f32 v3, v4, v3
	global_store_dwordx4 v[44:45], v[0:3], off offset:1024
	s_cbranch_scc1 .LBB0_1177
